# sharded-counter (64 x 4 arrivals) flat barrier replaces the hierarchical grid barrier after the first GEMM (all its stores are write-through)
# speedup vs baseline: 1.0033x; 1.0008x over previous
; __device__ __forceinline__ unsigned xb_ld(unsigned* p)              { return __hip_atomic_load(p, __ATOMIC_RELAXED, __HIP_MEMORY_SCOPE_AGENT); }
; __device__ __forceinline__ unsigned xb_add(unsigned* p, unsigned v) { return __hip_atomic_fetch_add(p, v, __ATOMIC_RELAXED, __HIP_MEMORY_SCOPE_AGENT); }
; #define XB_SPIN(cond, bar) do { unsigned _sp = 0; while (cond) { __builtin_amdgcn_s_sleep(1); \
;     if ((++_sp & 255u) == 0u) { if (xb_ld(&(bar)[XB_TMO])) break; if (_sp > XB_SPIN_CAP) { atomicAdd(&(bar)[XB_TMO], 1u); break; } } } } while (0)
; __device__ __forceinline__ void xcd_barrier(const XcdBarrier& b) {
;     asm volatile("s_waitcnt vmcnt(0)" ::: "memory");
;     __syncthreads();
;     if (threadIdx.x == 0) {
;         unsigned* bar = b.bar;
;         __builtin_amdgcn_s_waitcnt(0);
;         unsigned nloc = b.st[0], nx = b.st[1];
;         if (nloc == 0u) { xcd_barrier_complete(bar, b.x, nloc, nx); b.st[0] = nloc; b.st[1] = nx; }
;         const unsigned old = xb_add(&bar[XB_XSUB(b.x)], 1u);
;         const unsigned gen = old / nloc;
;         if (old + 1u == (gen + 1u) * nloc) {
;             __builtin_amdgcn_fence(__ATOMIC_RELEASE, "agent");
;             asm volatile("s_waitcnt vmcnt(0)" ::: "memory");
;             const unsigned og = xb_add(&bar[XB_TOP], 1u);
;             const unsigned tg = og / nx;
;             if (og + 1u == (tg + 1u) * nx) xb_add(&bar[XB_TOPGEN], 1u);
;             else XB_SPIN(xb_ld(&bar[XB_TOPGEN]) == tg, bar);
;             __builtin_amdgcn_fence(__ATOMIC_ACQUIRE, "agent");
;             xb_add(&bar[XB_XGEN(b.x)], 1u);
;             asm volatile("s_waitcnt vmcnt(0)" ::: "memory");
;         } else {
;             XB_SPIN(xb_ld(&bar[XB_XGEN(b.x)]) == gen, bar);
;             __builtin_amdgcn_fence(__ATOMIC_ACQUIRE, "agent");
;             asm volatile("s_waitcnt vmcnt(0)" ::: "memory");
;         }
;     }
;     __syncthreads();
.LBB0_164:
	s_waitcnt vmcnt(0)
	s_waitcnt vmcnt(0)
	s_barrier
	s_cmp_eq_u32 s6, 0x100
	s_cbranch_scc0 .Lsh3_orig
	s_and_saveexec_b64 s[0:1], s[92:93]
	s_cbranch_execz .LBB0_216
	v_readlane_b32 s98, v249, 2
	s_and_b32 s98, s98, 63
	s_lshl_b32 s98, s98, 6
	s_add_i32 s98, s98, 0x2000
	v_mov_b32_e32 v250, s98
	v_mov_b32_e32 v251, 1
	global_atomic_add v250, v251, s[10:11]
	s_mov_b64 exec, -1
	v_lshlrev_b32_e32 v252, 6, v208
	v_add_u32_e32 v252, 0x2000, v252
.Lsh3_poll:
	global_load_dword v253, v252, s[10:11] sc1
	s_waitcnt vmcnt(0)
	v_cmp_gt_u32_e32 vcc, 4, v253
	s_nop 3
	s_cmp_eq_u64 vcc, 0
	s_cbranch_scc1 .Lsh3_pollend
	s_sleep 1
	s_branch .Lsh3_poll
.Lsh3_pollend:
	buffer_inv sc1
	s_waitcnt vmcnt(0)
	s_branch .LBB0_216
.Lsh3_orig:
	s_and_saveexec_b64 s[0:1], s[92:93]
	s_cbranch_execz .LBB0_216
	s_add_i32 s5, 0, 0x23fc0
	v_mov_b32_e32 v0, s5
	s_waitcnt vmcnt(0) expcnt(0) lgkmcnt(0)
	ds_read_b32 v2, v0
	s_add_i32 s5, 0, 0x23fc4
	v_mov_b32_e32 v0, s5
	ds_read_b32 v0, v0
	s_waitcnt lgkmcnt(1)
	v_cmp_ne_u32_e32 vcc, 0, v2
	s_cbranch_vccnz .LBB0_180
	s_mov_b32 s5, 1
	v_mov_b32_e32 v16, 0
	s_branch .LBB0_168
